# attention loop: one static s_setprio 1 for waves 4-7 (the later-dispatched half) across the whole KV loop, reset at loop exit
# speedup vs baseline: 1.0078x; 1.0078x over previous
; DI void attn_unit(const Params& p, LAS unsigned char* ldsu, int kind, int b, int h, int u, float lam) {
;     ...
;     f32x16 O[4]; float l = 0.f;
; #pragma unroll
;     for (int v = 0; v < 4; ++v)
; #pragma unroll
;         for (int i = 0; i < 16; ++i) O[v][i] = 0.f;
;     const int i16 = lane & 15, q4 = i16 >> 2, p4 = i16 & 3, blk = (lane >> 4) & 1;
;     const int kboff = qr * KRS + 16 * hh + cmp * 128, vboff = SLOT_V + (4 * hh + q4) * VRS + blk * 32 + p4 * 8;
;     ...
;     if (kind == 0) {
;         unsigned poff[5]; dma_offsets(poff, wid, lane);
;         auto stage = [&](int t) { if (t >= ntl) t = ntl - 1; const int row0 = t == 0 ? ROW_M : b * SEQ + (t - 1) * 64;
;             dma_tile(lds + (t & 3) * SLOT_B, KB + (size_t)row0 * 512 + hc, VB + (size_t)row0 * 512 + hc, poff, wid); };
;         stage(0); stage(1); stage(2);
;         asm volatile("s_waitcnt vmcnt(10)" ::: "memory");
;         __syncthreads();
.LBB0_743:
	s_add_i32 s6, s31, -1
	v_readlane_b32 s7, v254, 22
	s_add_u32 s22, s7, s62
	v_readlane_b32 s7, v254, 23
	s_addc_u32 s23, s7, 0
	v_readlane_b32 s7, v254, 24
	s_add_u32 s24, s7, s62
	v_readlane_b32 s7, v254, 25
	s_addc_u32 s25, s7, 0
	s_and_b64 s[10:11], s[0:1], exec
	v_lshlrev_b32_e32 v0, 10, v0
	v_min_i32_e32 v2, 15, v2
	s_cselect_b32 s21, s23, s25
	s_cselect_b32 s20, s22, s24
	s_lshl_b32 s7, s12, 10
	v_lshl_or_b32 v132, v2, 4, v0
	s_add_i32 s26, s7, 0
	s_mov_b32 s10, m0
	s_mov_b32 m0, s26
	s_nop 0
	global_load_lds_dwordx4 v132, s[20:21]
	s_mov_b32 m0, s10
	s_lshl_b32 s10, s13, 10
	s_add_i32 s27, s10, 0
	s_add_i32 s11, s27, 0x400
	v_lshlrev_b32_e32 v3, 10, v3
	v_min_i32_e32 v4, 15, v4
	s_and_b64 s[12:13], exec, s[8:9]
	v_lshl_or_b32 v131, v4, 4, v3
	s_mov_b32 s12, m0
	s_mov_b32 m0, s11
	s_nop 0
	global_load_lds_dwordx4 v131, s[20:21]
	s_mov_b32 m0, s12
	s_cselect_b32 s21, s23, s25
	s_cselect_b32 s20, s22, s24
	s_lshl_b32 s11, s18, 10
	s_add_i32 s22, s11, 0
	v_lshlrev_b32_e32 v5, 10, v5
	v_min_i32_e32 v6, 15, v6
	s_add_i32 s12, s22, 0x800
	v_lshl_or_b32 v130, v6, 4, v5
	s_mov_b32 s13, m0
	s_mov_b32 m0, s12
	s_nop 0
	global_load_lds_dwordx4 v130, s[20:21]
	s_mov_b32 m0, s13
	s_lshl_b32 s12, s19, 10
	s_add_i32 s23, s12, 0
	v_lshlrev_b32_e32 v7, 10, v7
	v_min_i32_e32 v8, 15, v8
	s_add_i32 s13, s23, 0xc00
	v_lshl_or_b32 v129, v8, 4, v7
	s_mov_b32 s18, m0
	s_mov_b32 m0, s13
	s_nop 0
	global_load_lds_dwordx4 v129, s[20:21]
	s_mov_b32 m0, s18
	s_lshl_b32 s13, s17, 10
	s_add_i32 s24, s13, 0
	v_lshlrev_b32_e32 v0, 10, v9
	v_min_i32_e32 v2, 15, v10
	s_add_i32 s17, s24, 0x1000
	v_lshl_or_b32 v133, v2, 4, v0
	s_mov_b32 s18, m0
	s_mov_b32 m0, s17
	s_nop 0
	global_load_lds_dwordx4 v133, s[20:21]
	s_mov_b32 m0, s18
	s_lshl_b32 s17, s16, 12
	s_sub_i32 s17, s17, 64
	s_lshl_b32 s16, s16, 22
	v_readlane_b32 s36, v254, 14
	s_add_u32 s18, s36, s16
	v_readlane_b32 s37, v254, 15
	s_addc_u32 s19, s37, 0
	s_add_u32 s20, s18, s62
	s_addc_u32 s21, s19, 0
	v_readlane_b32 s38, v254, 16
	s_add_u32 s18, s38, s16
	v_readlane_b32 s39, v254, 17
	s_addc_u32 s19, s39, 0
	s_add_u32 s25, s18, s62
	s_addc_u32 s34, s19, 0
	s_and_b64 s[18:19], s[0:1], exec
	s_cselect_b32 s19, s21, s34
	s_cselect_b32 s18, s20, s25
	s_add_i32 s26, s26, 0x9400
	s_mov_b32 s35, m0
	s_mov_b32 m0, s26
	s_nop 0
	global_load_lds_dwordx4 v132, s[18:19]
	s_mov_b32 m0, s35
	s_add_i32 s27, s27, 0x9800
	s_mov_b32 s26, m0
	s_mov_b32 m0, s27
	s_nop 0
	global_load_lds_dwordx4 v131, s[18:19]
	s_mov_b32 m0, s26
	s_and_b64 s[18:19], exec, s[8:9]
	s_cselect_b32 s19, s21, s34
	s_cselect_b32 s18, s20, s25
	s_add_i32 s22, s22, 0x9c00
	s_mov_b32 s20, m0
	s_mov_b32 m0, s22
	s_nop 0
	global_load_lds_dwordx4 v130, s[18:19]
	s_mov_b32 m0, s20
	s_add_i32 s23, s23, 0xa000
	s_mov_b32 s20, m0
	s_mov_b32 m0, s23
	s_nop 0
	global_load_lds_dwordx4 v129, s[18:19]
	s_mov_b32 m0, s20
	s_add_i32 s24, s24, 0xa400
	s_bitset1_b32 s16, 16
	s_mov_b32 s20, m0
	s_mov_b32 m0, s24
	s_nop 0
	global_load_lds_dwordx4 v133, s[18:19]
	s_mov_b32 m0, s20
	s_add_u32 s18, s36, s16
	s_addc_u32 s19, s37, 0
	s_add_u32 s20, s18, s62
	s_addc_u32 s21, s19, 0
	s_add_u32 s16, s38, s16
	s_addc_u32 s18, s39, 0
	s_add_u32 s16, s16, s62
	s_addc_u32 s22, s18, 0
	s_and_b64 s[18:19], s[0:1], exec
	v_readlane_b32 s25, v254, 30
	s_cselect_b32 s19, s21, s22
	s_cselect_b32 s18, s20, s16
	s_add_i32 s23, s25, s7
	s_mov_b32 s24, m0
	s_mov_b32 m0, s23
	s_nop 0
	global_load_lds_dwordx4 v132, s[18:19]
	s_mov_b32 m0, s24
	s_add_i32 s23, s25, s10
	s_addk_i32 s23, 0x400
	s_mov_b32 s24, m0
	s_mov_b32 m0, s23
	s_nop 0
	global_load_lds_dwordx4 v131, s[18:19]
	s_mov_b32 m0, s24
	s_and_b64 s[18:19], exec, s[8:9]
	s_cselect_b32 s19, s21, s22
	s_cselect_b32 s18, s20, s16
	s_add_i32 s16, s25, s11
	s_addk_i32 s16, 0x800
	s_mov_b32 s20, m0
	s_mov_b32 m0, s16
	s_nop 0
	global_load_lds_dwordx4 v130, s[18:19]
	s_mov_b32 m0, s20
	s_add_i32 s16, s25, s12
	s_addk_i32 s16, 0xc00
	s_mov_b32 s20, m0
	s_mov_b32 m0, s16
	s_nop 0
	global_load_lds_dwordx4 v129, s[18:19]
	s_mov_b32 m0, s20
	s_add_i32 s16, s25, s13
	s_addk_i32 s16, 0x1000
	s_mov_b32 s20, m0
	s_mov_b32 m0, s16
	s_nop 0
	global_load_lds_dwordx4 v133, s[18:19]
	s_mov_b32 m0, s20
	s_add_u32 s16, s36, s62
	s_waitcnt vmcnt(10)
	s_addc_u32 s18, s37, 0
	v_mov_b32_e32 v14, v1
	v_mov_b32_e32 v15, v1
	s_add_u32 s19, s38, s62
	v_mov_b32_e32 v0, v1
	v_mov_b32_e32 v2, v1
	v_mov_b32_e32 v3, v1
	v_mov_b32_e32 v4, v1
	v_mov_b32_e32 v5, v1
	v_mov_b32_e32 v6, v1
	v_mov_b32_e32 v7, v1
	v_mov_b32_e32 v8, v1
	v_mov_b32_e32 v9, v1
	v_mov_b32_e32 v10, v1
	v_mov_b32_e32 v11, v1
	v_mov_b32_e32 v12, v1
	v_mov_b32_e32 v13, v1
	v_mov_b64_e32 v[30:31], v[14:15]
	v_mov_b64_e32 v[46:47], v[14:15]
	v_mov_b64_e32 v[62:63], v[14:15]
	v_mov_b64_e32 v[78:79], v[14:15]
	s_addc_u32 s20, s39, 0
	v_add3_u32 v134, v176, v177, v178
	s_mov_b32 s21, 0
	v_mov_b32_e32 v175, 0
	v_mov_b64_e32 v[28:29], v[12:13]
	v_mov_b64_e32 v[26:27], v[10:11]
	v_mov_b64_e32 v[24:25], v[8:9]
	v_mov_b64_e32 v[22:23], v[6:7]
	v_mov_b64_e32 v[20:21], v[4:5]
	v_mov_b64_e32 v[18:19], v[2:3]
	v_mov_b64_e32 v[16:17], v[0:1]
	v_mov_b64_e32 v[44:45], v[12:13]
	v_mov_b64_e32 v[42:43], v[10:11]
	v_mov_b64_e32 v[40:41], v[8:9]
	v_mov_b64_e32 v[38:39], v[6:7]
	v_mov_b64_e32 v[36:37], v[4:5]
	v_mov_b64_e32 v[34:35], v[2:3]
	v_mov_b64_e32 v[32:33], v[0:1]
	v_mov_b64_e32 v[60:61], v[12:13]
	v_mov_b64_e32 v[58:59], v[10:11]
	v_mov_b64_e32 v[56:57], v[8:9]
	v_mov_b64_e32 v[54:55], v[6:7]
	v_mov_b64_e32 v[52:53], v[4:5]
	v_mov_b64_e32 v[50:51], v[2:3]
	v_mov_b64_e32 v[48:49], v[0:1]
	v_mov_b64_e32 v[76:77], v[12:13]
	v_mov_b64_e32 v[74:75], v[10:11]
	v_mov_b64_e32 v[72:73], v[8:9]
	v_mov_b64_e32 v[70:71], v[6:7]
	v_mov_b64_e32 v[68:69], v[4:5]
	v_mov_b64_e32 v[66:67], v[2:3]
	v_mov_b64_e32 v[64:65], v[0:1]
	s_waitcnt lgkmcnt(0)
	s_barrier
	s_and_b64 vcc, exec, s[0:1]
	s_cbranch_vccnz .LBB0_745
	s_setprio 1
	s_barrier
	s_branch .LBB0_745

; DI void attn_unit(const Params& p, LAS unsigned char* ldsu, int kind, int b, int h, int u, float lam) {
;     ...
;     asm volatile("s_waitcnt vmcnt(0)" ::: "memory");
;     __syncthreads();
.Lattn_exit:
	s_setprio 0
	s_and_b64 vcc, exec, s[0:1]
	s_cbranch_vccz .LBB0_747
	s_barrier
	s_branch .LBB0_747
